# ev second butterfly step (lane^16) via v_permlane16_swap instead of cndmask+bpermute, on top of stack11
# baseline (speedup 1.0000x reference)
; #define EV_IDS(t, i0, i1, c0, c1) do { i0 = sel_i[(size_t)(t) * 128 + lane]; i1 = sel_i[(size_t)(t) * 128 + 64 + lane]; \
;                                        c0 = cbuf[(size_t)(t) * 128 + lane]; c1 = cbuf[(size_t)(t) * 128 + 64 + lane]; } while (0)
; DI void ev_load(const unsigned char* __restrict__ vb8, const int id0, const int id1, const int cs, const int lane, uint4 (&v)[16]) {
; #pragma unroll
;   for (int i = 0; i < 16; ++i) {
;     const int id = __shfl(i < 8 ? id0 : id1, (8 * i + (lane >> 3)) & 63, 64);
;     v[i] = *(const uint4*)(vb8 + (size_t)id * 1024 + 128 * cs + 16 * (lane & 7));
;   }
; }
; DI void ev_compute(const uint4 (&v)[16], const float c0, const float c1, u16* __restrict__ yrow, const int lane) {
;   f32x2 acc[8];
; #pragma unroll
;   for (int k = 0; k < 8; ++k) acc[k] = f32x2{0.f, 0.f};
; #pragma unroll
;   for (int i = 0; i < 16; ++i) {
;     const float c = __shfl(i < 8 ? c0 : c1, (8 * i + (lane >> 3)) & 63, 64);
;     const f32x2 cc = f32x2{c, c};
;     f32x2 vf[8];
;     fp8x16_to_f32(v[i], vf);
; #pragma unroll
;     for (int k = 0; k < 8; ++k) acc[k] = __builtin_elementwise_fma(vf[k], cc, acc[k]);
;   }
; DI void phase_ev(const Params& p, const unsigned my_xcc, const unsigned my_rank) {
;     ...
;     for (int k = 0; k < K; k += 2) {
;       ev_load(vb8, b0, b1, cs, lane, vB);
;       const int tA2 = TOK(k + 2); int na0, na1; float nca0, nca1;
;       EV_IDS(tA2, na0, na1, nca0, nca1);
;       ev_compute(vA, ca0, ca1, ybuf + (size_t)tA * 1024 + 128 * cs, lane);
;       ev_load(vb8, na0, na1, cs, lane, vA);
;       const int tB2 = TOK(k + 3); int nb0, nb1; float ncb0, ncb1;
;       EV_IDS(tB2, nb0, nb1, ncb0, ncb1);
;       ev_compute(vB, cb0, cb1, ybuf + (size_t)tB * 1024 + 128 * cs, lane);
;       tA = tA2; a0 = na0; a1 = na1; ca0 = nca0; ca1 = nca1; tB = tB2; b0 = nb0; b1 = nb1; cb0 = ncb0; cb1 = ncb1;
.LBB0_570:
	s_add_i32 s24, s19, -1
	s_min_i32 s0, s24, s41
	s_waitcnt vmcnt(2)
	ds_bpermute_b32 v66, v168, v185
	s_mul_i32 s0, s0, s39
	s_add_i32 s0, s0, s33
	s_lshl_b32 s0, s0, 3
	s_add_i32 s20, s0, s38
	s_ashr_i32 s21, s20, 31
	s_waitcnt lgkmcnt(0)
	s_lshl_b64 s[0:1], s[20:21], 9
	v_or_b32_e32 v158, s0, v174
	v_mov_b32_e32 v159, s1
	v_lshl_add_u32 v66, v66, 10, v204
	v_lshl_add_u64 v[156:157], s[26:27], 0, v[158:159]
	global_load_dwordx4 v[126:129], v66, s[98:99]
	v_or_b32_e32 v160, 0x100, v158
	global_load_dword v157, v[156:157], off
	ds_bpermute_b32 v66, v169, v185
	v_lshl_add_u64 v[158:159], s[28:29], 0, v[158:159]
	global_load_dword v181, v[158:159], off
	v_mov_b32_e32 v161, s1
	v_lshl_add_u64 v[158:159], s[28:29], 0, v[160:161]
	s_waitcnt lgkmcnt(0)
	v_lshl_add_u32 v66, v66, 10, v204
	global_load_dwordx4 v[122:125], v66, s[98:99]
	ds_bpermute_b32 v66, v170, v185
	global_load_dword v182, v[158:159], off
	v_lshl_add_u64 v[162:163], s[26:27], 0, v[160:161]
	s_waitcnt vmcnt(5)
	ds_bpermute_b32 v158, v168, v155
	v_cvt_pk_f32_fp8_e32 v[160:161], v62
	s_waitcnt lgkmcnt(1)
	v_lshl_add_u32 v66, v66, 10, v204
	global_load_dwordx4 v[118:121], v66, s[98:99]
	ds_bpermute_b32 v66, v171, v185
	global_load_dword v156, v[162:163], off
	v_cvt_pk_f32_fp8_sdwa v[162:163], v62 src0_sel:WORD_1
	v_cvt_pk_f32_fp8_e32 v[164:165], v63
	v_cvt_pk_f32_fp8_sdwa v[62:63], v63 src0_sel:WORD_1
	s_waitcnt lgkmcnt(0)
	v_lshl_add_u32 v66, v66, 10, v204
	global_load_dwordx4 v[114:117], v66, s[98:99]
	ds_bpermute_b32 v66, v172, v185
	v_cvt_pk_f32_fp8_sdwa v[186:187], v64 src0_sel:WORD_1
	v_cvt_pk_f32_fp8_e32 v[188:189], v65
	v_pk_fma_f32 v[160:161], v[160:161], v[158:159], 0 op_sel_hi:[1,0,0]
	v_pk_fma_f32 v[162:163], v[162:163], v[158:159], 0 op_sel_hi:[1,0,0]
	s_waitcnt lgkmcnt(0)
	v_lshl_add_u32 v66, v66, 10, v204
	global_load_dwordx4 v[110:113], v66, s[98:99]
	ds_bpermute_b32 v66, v173, v185
	v_pk_fma_f32 v[164:165], v[164:165], v[158:159], 0 op_sel_hi:[1,0,0]
	v_pk_fma_f32 v[62:63], v[62:63], v[158:159], 0 op_sel_hi:[1,0,0]
	v_pk_fma_f32 v[186:187], v[186:187], v[158:159], 0 op_sel_hi:[1,0,0]
	v_pk_fma_f32 v[188:189], v[188:189], v[158:159], 0 op_sel_hi:[1,0,0]
	s_waitcnt lgkmcnt(0)
	v_lshl_add_u32 v66, v66, 10, v204
	global_load_dwordx4 v[106:109], v66, s[98:99]
	ds_bpermute_b32 v66, v175, v185
	v_cvt_pk_f32_fp8_e32 v[196:197], v60
	v_cvt_pk_f32_fp8_sdwa v[198:199], v60 src0_sel:WORD_1
	v_cvt_pk_f32_fp8_e32 v[202:203], v61
	v_cvt_pk_f32_fp8_sdwa v[60:61], v61 src0_sel:WORD_1
	s_waitcnt lgkmcnt(0)
	v_lshl_add_u32 v66, v66, 10, v204
	global_load_dwordx4 v[102:105], v66, s[98:99]
	ds_bpermute_b32 v66, v176, v185
	v_cvt_pk_f32_fp8_e32 v[190:191], v58
	v_cvt_pk_f32_fp8_sdwa v[192:193], v58 src0_sel:WORD_1
	v_cvt_pk_f32_fp8_e32 v[194:195], v59
	v_cvt_pk_f32_fp8_sdwa v[58:59], v59 src0_sel:WORD_1
	s_waitcnt lgkmcnt(0)
	v_lshl_add_u32 v66, v66, 10, v204
	global_load_dwordx4 v[98:101], v66, s[98:99]
	ds_bpermute_b32 v66, v168, v184
	s_ashr_i32 s37, s36, 31
	s_lshl_b64 s[34:35], s[36:37], 11
	s_min_i32 s0, s19, s41
	s_mul_i32 s0, s0, s39
	s_waitcnt lgkmcnt(0)
	v_lshl_add_u32 v66, v66, 10, v204
	global_load_dwordx4 v[94:97], v66, s[98:99]
	ds_bpermute_b32 v66, v169, v184
	s_add_i32 s0, s0, s33
	s_lshl_b32 s0, s0, 3
	ds_bpermute_b32 v166, v169, v183
	s_ashr_i32 s31, s30, 31
	s_waitcnt lgkmcnt(1)
	v_lshl_add_u32 v66, v66, 10, v204
	global_load_dwordx4 v[90:93], v66, s[98:99]
	ds_bpermute_b32 v66, v170, v184
	s_lshl_b64 s[30:31], s[30:31], 11
	s_add_i32 s19, s19, 2
	s_mov_b32 s36, s20
	s_waitcnt lgkmcnt(0)
	v_lshl_add_u32 v66, v66, 10, v204
	global_load_dwordx4 v[86:89], v66, s[98:99]
	ds_bpermute_b32 v66, v171, v184
	s_waitcnt lgkmcnt(0)
	v_lshl_add_u32 v66, v66, 10, v204
	global_load_dwordx4 v[82:85], v66, s[98:99]
	ds_bpermute_b32 v66, v172, v184
	s_waitcnt lgkmcnt(0)
	v_lshl_add_u32 v66, v66, 10, v204
	global_load_dwordx4 v[78:81], v66, s[98:99]
	ds_bpermute_b32 v66, v173, v184
	s_waitcnt lgkmcnt(0)
	v_lshl_add_u32 v66, v66, 10, v204
	global_load_dwordx4 v[74:77], v66, s[98:99]
	ds_bpermute_b32 v66, v175, v184
	s_waitcnt lgkmcnt(0)
	v_lshl_add_u32 v66, v66, 10, v204
	global_load_dwordx4 v[70:73], v66, s[98:99]
	ds_bpermute_b32 v66, v176, v184
	v_cvt_pk_f32_fp8_e32 v[184:185], v64
	v_cvt_pk_f32_fp8_sdwa v[64:65], v65 src0_sel:WORD_1
	v_pk_fma_f32 v[184:185], v[184:185], v[158:159], 0 op_sel_hi:[1,0,0]
	v_pk_fma_f32 v[64:65], v[64:65], v[158:159], 0 op_sel_hi:[1,0,0]
	ds_bpermute_b32 v158, v169, v155
	s_waitcnt lgkmcnt(1)
	v_lshl_add_u32 v66, v66, 10, v204
	global_load_dwordx4 v[66:69], v66, s[98:99]
	s_waitcnt lgkmcnt(0)
	v_pk_fma_f32 v[60:61], v[60:61], v[158:159], v[64:65] op_sel_hi:[1,0,1]
	ds_bpermute_b32 v64, v170, v155
	v_pk_fma_f32 v[162:163], v[192:193], v[158:159], v[162:163] op_sel_hi:[1,0,1]
	v_pk_fma_f32 v[164:165], v[194:195], v[158:159], v[164:165] op_sel_hi:[1,0,1]
	v_pk_fma_f32 v[58:59], v[58:59], v[158:159], v[62:63] op_sel_hi:[1,0,1]
	v_pk_fma_f32 v[62:63], v[196:197], v[158:159], v[184:185] op_sel_hi:[1,0,1]
	v_cvt_pk_f32_fp8_e32 v[192:193], v56
	v_cvt_pk_f32_fp8_sdwa v[194:195], v56 src0_sel:WORD_1
	v_cvt_pk_f32_fp8_e32 v[196:197], v57
	v_cvt_pk_f32_fp8_sdwa v[56:57], v57 src0_sel:WORD_1
	v_pk_fma_f32 v[160:161], v[190:191], v[158:159], v[160:161] op_sel_hi:[1,0,1]
	v_pk_fma_f32 v[184:185], v[198:199], v[158:159], v[186:187] op_sel_hi:[1,0,1]
	v_pk_fma_f32 v[186:187], v[202:203], v[158:159], v[188:189] op_sel_hi:[1,0,1]
	v_cvt_pk_f32_fp8_e32 v[158:159], v54
	v_cvt_pk_f32_fp8_sdwa v[188:189], v54 src0_sel:WORD_1
	v_cvt_pk_f32_fp8_e32 v[190:191], v55
	v_cvt_pk_f32_fp8_sdwa v[54:55], v55 src0_sel:WORD_1
	s_waitcnt lgkmcnt(0)
; DI void ev_compute(const uint4 (&v)[16], const float c0, const float c1, u16* __restrict__ yrow, const int lane) {
;   f32x2 acc[8];
; #pragma unroll
;   for (int k = 0; k < 8; ++k) acc[k] = f32x2{0.f, 0.f};
; #pragma unroll
;   for (int i = 0; i < 16; ++i) {
;     const float c = __shfl(i < 8 ? c0 : c1, (8 * i + (lane >> 3)) & 63, 64);
;     const f32x2 cc = f32x2{c, c};
;     f32x2 vf[8];
;     fp8x16_to_f32(v[i], vf);
; #pragma unroll
;     for (int k = 0; k < 8; ++k) acc[k] = __builtin_elementwise_fma(vf[k], cc, acc[k]);
;   }
	v_pk_fma_f32 v[56:57], v[56:57], v[64:65], v[60:61] op_sel_hi:[1,0,1]
	ds_bpermute_b32 v60, v171, v155
	v_pk_fma_f32 v[158:159], v[158:159], v[64:65], v[160:161] op_sel_hi:[1,0,1]
	v_pk_fma_f32 v[160:161], v[188:189], v[64:65], v[162:163] op_sel_hi:[1,0,1]
	v_pk_fma_f32 v[162:163], v[190:191], v[64:65], v[164:165] op_sel_hi:[1,0,1]
	v_pk_fma_f32 v[54:55], v[54:55], v[64:65], v[58:59] op_sel_hi:[1,0,1]
	v_pk_fma_f32 v[58:59], v[192:193], v[64:65], v[62:63] op_sel_hi:[1,0,1]
	v_cvt_pk_f32_fp8_e32 v[188:189], v52
	v_cvt_pk_f32_fp8_sdwa v[190:191], v52 src0_sel:WORD_1
	v_cvt_pk_f32_fp8_e32 v[192:193], v53
	v_cvt_pk_f32_fp8_sdwa v[52:53], v53 src0_sel:WORD_1
	v_pk_fma_f32 v[62:63], v[194:195], v[64:65], v[184:185] op_sel_hi:[1,0,1]
	v_pk_fma_f32 v[164:165], v[196:197], v[64:65], v[186:187] op_sel_hi:[1,0,1]
	v_cvt_pk_f32_fp8_e32 v[64:65], v50
	v_cvt_pk_f32_fp8_sdwa v[184:185], v50 src0_sel:WORD_1
	v_cvt_pk_f32_fp8_e32 v[186:187], v51
	v_cvt_pk_f32_fp8_sdwa v[50:51], v51 src0_sel:WORD_1
	s_waitcnt lgkmcnt(0)
	v_pk_fma_f32 v[52:53], v[52:53], v[60:61], v[56:57] op_sel_hi:[1,0,1]
	ds_bpermute_b32 v56, v172, v155
	v_pk_fma_f32 v[64:65], v[64:65], v[60:61], v[158:159] op_sel_hi:[1,0,1]
	v_pk_fma_f32 v[158:159], v[184:185], v[60:61], v[160:161] op_sel_hi:[1,0,1]
	v_pk_fma_f32 v[160:161], v[186:187], v[60:61], v[162:163] op_sel_hi:[1,0,1]
	v_pk_fma_f32 v[50:51], v[50:51], v[60:61], v[54:55] op_sel_hi:[1,0,1]
	v_pk_fma_f32 v[54:55], v[188:189], v[60:61], v[58:59] op_sel_hi:[1,0,1]
	v_cvt_pk_f32_fp8_e32 v[184:185], v48
	v_cvt_pk_f32_fp8_sdwa v[186:187], v48 src0_sel:WORD_1
	v_cvt_pk_f32_fp8_e32 v[188:189], v49
	v_cvt_pk_f32_fp8_sdwa v[48:49], v49 src0_sel:WORD_1
	v_pk_fma_f32 v[58:59], v[190:191], v[60:61], v[62:63] op_sel_hi:[1,0,1]
	v_pk_fma_f32 v[62:63], v[192:193], v[60:61], v[164:165] op_sel_hi:[1,0,1]
	v_cvt_pk_f32_fp8_e32 v[60:61], v46
	v_cvt_pk_f32_fp8_sdwa v[162:163], v46 src0_sel:WORD_1
	v_cvt_pk_f32_fp8_e32 v[164:165], v47
	v_cvt_pk_f32_fp8_sdwa v[46:47], v47 src0_sel:WORD_1
	s_waitcnt lgkmcnt(0)
	v_pk_fma_f32 v[48:49], v[48:49], v[56:57], v[52:53] op_sel_hi:[1,0,1]
	ds_bpermute_b32 v52, v173, v155
	v_pk_fma_f32 v[60:61], v[60:61], v[56:57], v[64:65] op_sel_hi:[1,0,1]
	v_pk_fma_f32 v[64:65], v[162:163], v[56:57], v[158:159] op_sel_hi:[1,0,1]
	v_pk_fma_f32 v[158:159], v[164:165], v[56:57], v[160:161] op_sel_hi:[1,0,1]
	v_pk_fma_f32 v[46:47], v[46:47], v[56:57], v[50:51] op_sel_hi:[1,0,1]
	v_pk_fma_f32 v[50:51], v[184:185], v[56:57], v[54:55] op_sel_hi:[1,0,1]
	v_cvt_pk_f32_fp8_e32 v[162:163], v44
	v_cvt_pk_f32_fp8_sdwa v[164:165], v44 src0_sel:WORD_1
	v_cvt_pk_f32_fp8_e32 v[184:185], v45
	v_cvt_pk_f32_fp8_sdwa v[44:45], v45 src0_sel:WORD_1
	v_pk_fma_f32 v[54:55], v[186:187], v[56:57], v[58:59] op_sel_hi:[1,0,1]
	v_pk_fma_f32 v[58:59], v[188:189], v[56:57], v[62:63] op_sel_hi:[1,0,1]
	v_cvt_pk_f32_fp8_e32 v[56:57], v42
	v_cvt_pk_f32_fp8_sdwa v[62:63], v42 src0_sel:WORD_1
	v_cvt_pk_f32_fp8_e32 v[160:161], v43
	v_cvt_pk_f32_fp8_sdwa v[42:43], v43 src0_sel:WORD_1
	s_waitcnt lgkmcnt(0)
	v_pk_fma_f32 v[44:45], v[44:45], v[52:53], v[48:49] op_sel_hi:[1,0,1]
	ds_bpermute_b32 v48, v175, v155
	v_pk_fma_f32 v[56:57], v[56:57], v[52:53], v[60:61] op_sel_hi:[1,0,1]
	v_pk_fma_f32 v[60:61], v[62:63], v[52:53], v[64:65] op_sel_hi:[1,0,1]
	v_pk_fma_f32 v[62:63], v[160:161], v[52:53], v[158:159] op_sel_hi:[1,0,1]
	v_pk_fma_f32 v[42:43], v[42:43], v[52:53], v[46:47] op_sel_hi:[1,0,1]
	v_pk_fma_f32 v[46:47], v[162:163], v[52:53], v[50:51] op_sel_hi:[1,0,1]
	v_cvt_pk_f32_fp8_e32 v[158:159], v40
	v_cvt_pk_f32_fp8_sdwa v[160:161], v40 src0_sel:WORD_1
	v_cvt_pk_f32_fp8_e32 v[162:163], v41
	v_cvt_pk_f32_fp8_sdwa v[40:41], v41 src0_sel:WORD_1
	v_pk_fma_f32 v[50:51], v[164:165], v[52:53], v[54:55] op_sel_hi:[1,0,1]
	v_pk_fma_f32 v[54:55], v[184:185], v[52:53], v[58:59] op_sel_hi:[1,0,1]
	v_cvt_pk_f32_fp8_e32 v[52:53], v38
	v_cvt_pk_f32_fp8_sdwa v[58:59], v38 src0_sel:WORD_1
	v_cvt_pk_f32_fp8_e32 v[64:65], v39
	v_cvt_pk_f32_fp8_sdwa v[38:39], v39 src0_sel:WORD_1
	s_waitcnt lgkmcnt(0)
	v_pk_fma_f32 v[40:41], v[40:41], v[48:49], v[44:45] op_sel_hi:[1,0,1]
	ds_bpermute_b32 v44, v176, v155
	v_pk_fma_f32 v[52:53], v[52:53], v[48:49], v[56:57] op_sel_hi:[1,0,1]
	v_pk_fma_f32 v[56:57], v[58:59], v[48:49], v[60:61] op_sel_hi:[1,0,1]
	v_pk_fma_f32 v[58:59], v[64:65], v[48:49], v[62:63] op_sel_hi:[1,0,1]
	v_pk_fma_f32 v[38:39], v[38:39], v[48:49], v[42:43] op_sel_hi:[1,0,1]
	v_pk_fma_f32 v[42:43], v[158:159], v[48:49], v[46:47] op_sel_hi:[1,0,1]
	v_cvt_pk_f32_fp8_e32 v[62:63], v36
	v_cvt_pk_f32_fp8_sdwa v[64:65], v36 src0_sel:WORD_1
	v_cvt_pk_f32_fp8_e32 v[158:159], v37
	v_cvt_pk_f32_fp8_sdwa v[36:37], v37 src0_sel:WORD_1
	v_pk_fma_f32 v[46:47], v[160:161], v[48:49], v[50:51] op_sel_hi:[1,0,1]
	v_pk_fma_f32 v[50:51], v[162:163], v[48:49], v[54:55] op_sel_hi:[1,0,1]
	v_cvt_pk_f32_fp8_e32 v[48:49], v34
	v_cvt_pk_f32_fp8_sdwa v[54:55], v34 src0_sel:WORD_1
	v_cvt_pk_f32_fp8_e32 v[60:61], v35
	v_cvt_pk_f32_fp8_sdwa v[34:35], v35 src0_sel:WORD_1
	s_waitcnt lgkmcnt(0)
	v_pk_fma_f32 v[36:37], v[36:37], v[44:45], v[40:41] op_sel_hi:[1,0,1]
	ds_bpermute_b32 v40, v168, v154
	v_pk_fma_f32 v[48:49], v[48:49], v[44:45], v[52:53] op_sel_hi:[1,0,1]
	v_pk_fma_f32 v[52:53], v[54:55], v[44:45], v[56:57] op_sel_hi:[1,0,1]
	v_pk_fma_f32 v[54:55], v[60:61], v[44:45], v[58:59] op_sel_hi:[1,0,1]
	v_pk_fma_f32 v[34:35], v[34:35], v[44:45], v[38:39] op_sel_hi:[1,0,1]
	v_pk_fma_f32 v[38:39], v[62:63], v[44:45], v[42:43] op_sel_hi:[1,0,1]
	v_cvt_pk_f32_fp8_e32 v[58:59], v32
	v_cvt_pk_f32_fp8_sdwa v[60:61], v32 src0_sel:WORD_1
	v_cvt_pk_f32_fp8_e32 v[62:63], v33
	v_cvt_pk_f32_fp8_sdwa v[32:33], v33 src0_sel:WORD_1
	v_pk_fma_f32 v[42:43], v[64:65], v[44:45], v[46:47] op_sel_hi:[1,0,1]
	v_pk_fma_f32 v[46:47], v[158:159], v[44:45], v[50:51] op_sel_hi:[1,0,1]
	v_cvt_pk_f32_fp8_e32 v[44:45], v30
	v_cvt_pk_f32_fp8_sdwa v[50:51], v30 src0_sel:WORD_1
	v_cvt_pk_f32_fp8_e32 v[56:57], v31
	v_cvt_pk_f32_fp8_sdwa v[30:31], v31 src0_sel:WORD_1
	s_waitcnt lgkmcnt(0)
; DI void ev_compute(const uint4 (&v)[16], const float c0, const float c1, u16* __restrict__ yrow, const int lane) {
;     ...
;   for (int i = 0; i < 16; ++i) {
;     const float c = __shfl(i < 8 ? c0 : c1, (8 * i + (lane >> 3)) & 63, 64);
;     const f32x2 cc = f32x2{c, c};
;     f32x2 vf[8];
;     fp8x16_to_f32(v[i], vf);
; #pragma unroll
;     for (int k = 0; k < 8; ++k) acc[k] = __builtin_elementwise_fma(vf[k], cc, acc[k]);
;   }
	v_pk_fma_f32 v[32:33], v[32:33], v[40:41], v[36:37] op_sel_hi:[1,0,1]
	ds_bpermute_b32 v36, v169, v154
	v_pk_fma_f32 v[44:45], v[44:45], v[40:41], v[48:49] op_sel_hi:[1,0,1]
	v_pk_fma_f32 v[48:49], v[50:51], v[40:41], v[52:53] op_sel_hi:[1,0,1]
	v_pk_fma_f32 v[50:51], v[56:57], v[40:41], v[54:55] op_sel_hi:[1,0,1]
	v_pk_fma_f32 v[30:31], v[30:31], v[40:41], v[34:35] op_sel_hi:[1,0,1]
	v_pk_fma_f32 v[34:35], v[58:59], v[40:41], v[38:39] op_sel_hi:[1,0,1]
	v_cvt_pk_f32_fp8_e32 v[54:55], v28
	v_cvt_pk_f32_fp8_sdwa v[56:57], v28 src0_sel:WORD_1
	v_cvt_pk_f32_fp8_e32 v[58:59], v29
	v_cvt_pk_f32_fp8_sdwa v[28:29], v29 src0_sel:WORD_1
	v_pk_fma_f32 v[38:39], v[60:61], v[40:41], v[42:43] op_sel_hi:[1,0,1]
	v_pk_fma_f32 v[42:43], v[62:63], v[40:41], v[46:47] op_sel_hi:[1,0,1]
	v_cvt_pk_f32_fp8_e32 v[40:41], v26
	v_cvt_pk_f32_fp8_sdwa v[46:47], v26 src0_sel:WORD_1
	v_cvt_pk_f32_fp8_e32 v[52:53], v27
	v_cvt_pk_f32_fp8_sdwa v[26:27], v27 src0_sel:WORD_1
	s_waitcnt lgkmcnt(0)
	v_pk_fma_f32 v[28:29], v[28:29], v[36:37], v[32:33] op_sel_hi:[1,0,1]
	ds_bpermute_b32 v32, v170, v154
	v_pk_fma_f32 v[40:41], v[40:41], v[36:37], v[44:45] op_sel_hi:[1,0,1]
	v_pk_fma_f32 v[44:45], v[46:47], v[36:37], v[48:49] op_sel_hi:[1,0,1]
	v_pk_fma_f32 v[46:47], v[52:53], v[36:37], v[50:51] op_sel_hi:[1,0,1]
	v_pk_fma_f32 v[26:27], v[26:27], v[36:37], v[30:31] op_sel_hi:[1,0,1]
	v_pk_fma_f32 v[30:31], v[54:55], v[36:37], v[34:35] op_sel_hi:[1,0,1]
	v_cvt_pk_f32_fp8_e32 v[50:51], v24
	v_cvt_pk_f32_fp8_sdwa v[52:53], v24 src0_sel:WORD_1
	v_cvt_pk_f32_fp8_e32 v[54:55], v25
	v_cvt_pk_f32_fp8_sdwa v[24:25], v25 src0_sel:WORD_1
	v_pk_fma_f32 v[34:35], v[56:57], v[36:37], v[38:39] op_sel_hi:[1,0,1]
	v_pk_fma_f32 v[38:39], v[58:59], v[36:37], v[42:43] op_sel_hi:[1,0,1]
	v_cvt_pk_f32_fp8_e32 v[36:37], v22
	v_cvt_pk_f32_fp8_sdwa v[42:43], v22 src0_sel:WORD_1
	v_cvt_pk_f32_fp8_e32 v[48:49], v23
	v_cvt_pk_f32_fp8_sdwa v[22:23], v23 src0_sel:WORD_1
	s_waitcnt lgkmcnt(0)
	v_pk_fma_f32 v[24:25], v[24:25], v[32:33], v[28:29] op_sel_hi:[1,0,1]
	ds_bpermute_b32 v28, v171, v154
	v_pk_fma_f32 v[36:37], v[36:37], v[32:33], v[40:41] op_sel_hi:[1,0,1]
	v_pk_fma_f32 v[40:41], v[42:43], v[32:33], v[44:45] op_sel_hi:[1,0,1]
	v_pk_fma_f32 v[42:43], v[48:49], v[32:33], v[46:47] op_sel_hi:[1,0,1]
	v_pk_fma_f32 v[22:23], v[22:23], v[32:33], v[26:27] op_sel_hi:[1,0,1]
	v_pk_fma_f32 v[26:27], v[50:51], v[32:33], v[30:31] op_sel_hi:[1,0,1]
	v_cvt_pk_f32_fp8_e32 v[46:47], v20
	v_cvt_pk_f32_fp8_sdwa v[48:49], v20 src0_sel:WORD_1
	v_cvt_pk_f32_fp8_e32 v[50:51], v21
	v_cvt_pk_f32_fp8_sdwa v[20:21], v21 src0_sel:WORD_1
	v_pk_fma_f32 v[30:31], v[52:53], v[32:33], v[34:35] op_sel_hi:[1,0,1]
	v_pk_fma_f32 v[34:35], v[54:55], v[32:33], v[38:39] op_sel_hi:[1,0,1]
	v_cvt_pk_f32_fp8_e32 v[32:33], v18
	v_cvt_pk_f32_fp8_sdwa v[38:39], v18 src0_sel:WORD_1
	v_cvt_pk_f32_fp8_e32 v[44:45], v19
	v_cvt_pk_f32_fp8_sdwa v[18:19], v19 src0_sel:WORD_1
	s_waitcnt lgkmcnt(0)
	v_pk_fma_f32 v[20:21], v[20:21], v[28:29], v[24:25] op_sel_hi:[1,0,1]
	ds_bpermute_b32 v24, v172, v154
	v_pk_fma_f32 v[32:33], v[32:33], v[28:29], v[36:37] op_sel_hi:[1,0,1]
	v_pk_fma_f32 v[36:37], v[38:39], v[28:29], v[40:41] op_sel_hi:[1,0,1]
	v_pk_fma_f32 v[38:39], v[44:45], v[28:29], v[42:43] op_sel_hi:[1,0,1]
	v_pk_fma_f32 v[18:19], v[18:19], v[28:29], v[22:23] op_sel_hi:[1,0,1]
	v_pk_fma_f32 v[22:23], v[46:47], v[28:29], v[26:27] op_sel_hi:[1,0,1]
	v_cvt_pk_f32_fp8_e32 v[42:43], v16
	v_cvt_pk_f32_fp8_sdwa v[44:45], v16 src0_sel:WORD_1
	v_cvt_pk_f32_fp8_e32 v[46:47], v17
	v_cvt_pk_f32_fp8_sdwa v[16:17], v17 src0_sel:WORD_1
	v_pk_fma_f32 v[26:27], v[48:49], v[28:29], v[30:31] op_sel_hi:[1,0,1]
	v_pk_fma_f32 v[30:31], v[50:51], v[28:29], v[34:35] op_sel_hi:[1,0,1]
	v_cvt_pk_f32_fp8_e32 v[28:29], v14
	v_cvt_pk_f32_fp8_sdwa v[34:35], v14 src0_sel:WORD_1
	v_cvt_pk_f32_fp8_e32 v[40:41], v15
	v_cvt_pk_f32_fp8_sdwa v[14:15], v15 src0_sel:WORD_1
	s_waitcnt lgkmcnt(0)
	v_pk_fma_f32 v[16:17], v[16:17], v[24:25], v[20:21] op_sel_hi:[1,0,1]
	ds_bpermute_b32 v20, v173, v154
	v_pk_fma_f32 v[28:29], v[28:29], v[24:25], v[32:33] op_sel_hi:[1,0,1]
	v_pk_fma_f32 v[32:33], v[34:35], v[24:25], v[36:37] op_sel_hi:[1,0,1]
	v_pk_fma_f32 v[34:35], v[40:41], v[24:25], v[38:39] op_sel_hi:[1,0,1]
	v_pk_fma_f32 v[14:15], v[14:15], v[24:25], v[18:19] op_sel_hi:[1,0,1]
	v_pk_fma_f32 v[18:19], v[42:43], v[24:25], v[22:23] op_sel_hi:[1,0,1]
	v_cvt_pk_f32_fp8_e32 v[38:39], v12
	v_cvt_pk_f32_fp8_sdwa v[40:41], v12 src0_sel:WORD_1
	v_cvt_pk_f32_fp8_e32 v[42:43], v13
	v_cvt_pk_f32_fp8_sdwa v[12:13], v13 src0_sel:WORD_1
	v_pk_fma_f32 v[22:23], v[44:45], v[24:25], v[26:27] op_sel_hi:[1,0,1]
	v_pk_fma_f32 v[26:27], v[46:47], v[24:25], v[30:31] op_sel_hi:[1,0,1]
	v_cvt_pk_f32_fp8_e32 v[24:25], v10
	v_cvt_pk_f32_fp8_sdwa v[30:31], v10 src0_sel:WORD_1
	v_cvt_pk_f32_fp8_e32 v[36:37], v11
	v_cvt_pk_f32_fp8_sdwa v[10:11], v11 src0_sel:WORD_1
	s_waitcnt lgkmcnt(0)
	v_pk_fma_f32 v[12:13], v[12:13], v[20:21], v[16:17] op_sel_hi:[1,0,1]
	ds_bpermute_b32 v16, v175, v154
	v_pk_fma_f32 v[24:25], v[24:25], v[20:21], v[28:29] op_sel_hi:[1,0,1]
	v_pk_fma_f32 v[28:29], v[30:31], v[20:21], v[32:33] op_sel_hi:[1,0,1]
	v_pk_fma_f32 v[30:31], v[36:37], v[20:21], v[34:35] op_sel_hi:[1,0,1]
	v_pk_fma_f32 v[10:11], v[10:11], v[20:21], v[14:15] op_sel_hi:[1,0,1]
	v_pk_fma_f32 v[14:15], v[38:39], v[20:21], v[18:19] op_sel_hi:[1,0,1]
	v_cvt_pk_f32_fp8_e32 v[34:35], v8
	v_cvt_pk_f32_fp8_sdwa v[36:37], v8 src0_sel:WORD_1
	v_cvt_pk_f32_fp8_e32 v[38:39], v9
	v_cvt_pk_f32_fp8_sdwa v[8:9], v9 src0_sel:WORD_1
	v_pk_fma_f32 v[18:19], v[40:41], v[20:21], v[22:23] op_sel_hi:[1,0,1]
	v_pk_fma_f32 v[22:23], v[42:43], v[20:21], v[26:27] op_sel_hi:[1,0,1]
	v_cvt_pk_f32_fp8_e32 v[20:21], v6
	v_cvt_pk_f32_fp8_sdwa v[26:27], v6 src0_sel:WORD_1
	v_cvt_pk_f32_fp8_e32 v[32:33], v7
	v_cvt_pk_f32_fp8_sdwa v[6:7], v7 src0_sel:WORD_1
	s_waitcnt lgkmcnt(0)
; DI unsigned pack2(float a, float b) { const f32x2 v = {a, b}; const bf16x2_t r = __builtin_convertvector(v, bf16x2_t); return __builtin_bit_cast(unsigned, r); }
; DI void ev_load(const unsigned char* __restrict__ vb8, const int id0, const int id1, const int cs, const int lane, uint4 (&v)[16]) {
; #pragma unroll
;   for (int i = 0; i < 16; ++i) {
;     const int id = __shfl(i < 8 ? id0 : id1, (8 * i + (lane >> 3)) & 63, 64);
;     v[i] = *(const uint4*)(vb8 + (size_t)id * 1024 + 128 * cs + 16 * (lane & 7));
;   }
; DI void ev_compute(const uint4 (&v)[16], const float c0, const float c1, u16* __restrict__ yrow, const int lane) {
;     ...
;   float a[16];
; #pragma unroll
;   for (int k = 0; k < 8; ++k) { a[2 * k] = acc[k][0]; a[2 * k + 1] = acc[k][1]; }
;   float q8[8], q4[4], q2[2];
;   const bool b5 = lane & 32, b4 = lane & 16, b3 = lane & 8;
; #pragma unroll
;   for (int j = 0; j < 8; ++j) { const float keep = b5 ? a[8 + j] : a[j], send = b5 ? a[j] : a[8 + j]; q8[j] = keep + __shfl_xor(send, 32, 64); }
; #pragma unroll
;   for (int j = 0; j < 4; ++j) { const float keep = b4 ? q8[4 + j] : q8[j], send = b4 ? q8[j] : q8[4 + j]; q4[j] = keep + __shfl_xor(send, 16, 64); }
; #pragma unroll
;   for (int j = 0; j < 2; ++j) { const float keep = b3 ? q4[2 + j] : q4[j], send = b3 ? q4[j] : q4[2 + j]; q2[j] = keep + __shfl_xor(send, 8, 64); }
;   *(unsigned*)(yrow + 16 * (lane & 7) + 2 * (lane >> 3)) = pack2(q2[0], q2[1]);
; }
	v_pk_fma_f32 v[8:9], v[8:9], v[16:17], v[12:13] op_sel_hi:[1,0,1]
	ds_bpermute_b32 v12, v176, v154
	v_pk_fma_f32 v[20:21], v[20:21], v[16:17], v[24:25] op_sel_hi:[1,0,1]
	v_pk_fma_f32 v[24:25], v[26:27], v[16:17], v[28:29] op_sel_hi:[1,0,1]
	v_pk_fma_f32 v[26:27], v[32:33], v[16:17], v[30:31] op_sel_hi:[1,0,1]
	v_pk_fma_f32 v[6:7], v[6:7], v[16:17], v[10:11] op_sel_hi:[1,0,1]
	v_pk_fma_f32 v[10:11], v[34:35], v[16:17], v[14:15] op_sel_hi:[1,0,1]
	v_pk_fma_f32 v[14:15], v[36:37], v[16:17], v[18:19] op_sel_hi:[1,0,1]
	v_pk_fma_f32 v[18:19], v[38:39], v[16:17], v[22:23] op_sel_hi:[1,0,1]
	v_cvt_pk_f32_fp8_e32 v[16:17], v2
	v_cvt_pk_f32_fp8_sdwa v[22:23], v2 src0_sel:WORD_1
	v_cvt_pk_f32_fp8_e32 v[28:29], v3
	v_cvt_pk_f32_fp8_sdwa v[2:3], v3 src0_sel:WORD_1
	v_cvt_pk_f32_fp8_e32 v[30:31], v4
	v_cvt_pk_f32_fp8_sdwa v[32:33], v4 src0_sel:WORD_1
	v_cvt_pk_f32_fp8_e32 v[34:35], v5
	v_cvt_pk_f32_fp8_sdwa v[4:5], v5 src0_sel:WORD_1
	s_waitcnt lgkmcnt(0)
	v_pk_fma_f32 v[16:17], v[16:17], v[12:13], v[20:21] op_sel_hi:[1,0,1]
	v_pk_fma_f32 v[2:3], v[2:3], v[12:13], v[6:7] op_sel_hi:[1,0,1]
	v_pk_fma_f32 v[6:7], v[30:31], v[12:13], v[10:11] op_sel_hi:[1,0,1]
	v_pk_fma_f32 v[20:21], v[22:23], v[12:13], v[24:25] op_sel_hi:[1,0,1]
	v_pk_fma_f32 v[22:23], v[28:29], v[12:13], v[26:27] op_sel_hi:[1,0,1]
	v_pk_fma_f32 v[10:11], v[32:33], v[12:13], v[14:15] op_sel_hi:[1,0,1]
	v_pk_fma_f32 v[14:15], v[34:35], v[12:13], v[18:19] op_sel_hi:[1,0,1]
	v_pk_fma_f32 v[4:5], v[4:5], v[12:13], v[8:9] op_sel_hi:[1,0,1]
	s_nop 1
	v_permlane32_swap_b32_e32 v16, v6
	v_permlane32_swap_b32_e32 v17, v7
	v_permlane32_swap_b32_e32 v20, v10
	v_permlane32_swap_b32_e32 v21, v11
	v_permlane32_swap_b32_e32 v22, v14
	v_permlane32_swap_b32_e32 v23, v15
	v_permlane32_swap_b32_e32 v2, v4
	v_permlane32_swap_b32_e32 v3, v5
	v_pk_add_f32 v[6:7], v[16:17], v[6:7]
	v_pk_add_f32 v[8:9], v[20:21], v[10:11]
	v_pk_add_f32 v[10:11], v[22:23], v[14:15]
	v_pk_add_f32 v[2:3], v[2:3], v[4:5]
	s_nop 1
	v_permlane16_swap_b32_e32 v6, v10
	v_permlane16_swap_b32_e32 v7, v11
	v_permlane16_swap_b32_e32 v8, v2
	v_permlane16_swap_b32_e32 v9, v3
	ds_bpermute_b32 v164, v168, v183
	s_waitcnt lgkmcnt(3)
	v_pk_add_f32 v[4:5], v[6:7], v[10:11]
	s_waitcnt vmcnt(19)
	v_cvt_pk_f32_fp8_sdwa v[160:161], v127 src0_sel:WORD_1
	s_waitcnt lgkmcnt(1)
	v_pk_add_f32 v[2:3], v[8:9], v[2:3]
	v_cvt_pk_f32_fp8_e32 v[162:163], v128
	v_cndmask_b32_e64 v6, v4, v2, s[10:11]
	v_cndmask_b32_e64 v8, v2, v4, s[10:11]
	v_cndmask_b32_e64 v2, v5, v3, s[10:11]
	ds_bpermute_b32 v6, v179, v6
	ds_bpermute_b32 v7, v179, v2
	v_cndmask_b32_e64 v9, v3, v5, s[10:11]
	v_cvt_pk_f32_fp8_sdwa v[188:189], v128 src0_sel:WORD_1
	v_cvt_pk_f32_fp8_e32 v[190:191], v129
	v_cvt_pk_f32_fp8_sdwa v[192:193], v129 src0_sel:WORD_1
	s_waitcnt lgkmcnt(0)
	v_pk_add_f32 v[2:3], v[8:9], v[6:7]
	s_waitcnt vmcnt(16)
	v_cvt_pk_f32_fp8_e32 v[194:195], v124
	v_cvt_pk_bf16_f32 v4, v2, v3
	v_lshl_add_u64 v[2:3], v[152:153], 0, s[34:35]
	global_store_dword v[2:3], v4, off
	ds_bpermute_b32 v2, v168, v157
	s_add_i32 s34, s0, s38
	s_ashr_i32 s35, s34, 31
	s_lshl_b64 s[0:1], s[34:35], 9
	v_or_b32_e32 v154, s0, v174
	s_waitcnt lgkmcnt(0)
	v_lshl_add_u32 v2, v2, 10, v204
	global_load_dwordx4 v[62:65], v2, s[98:99]
	ds_bpermute_b32 v2, v169, v157
	v_mov_b32_e32 v155, s1
	v_cvt_pk_f32_fp8_sdwa v[196:197], v124 src0_sel:WORD_1
	v_cvt_pk_f32_fp8_e32 v[198:199], v125
	v_cvt_pk_f32_fp8_sdwa v[124:125], v125 src0_sel:WORD_1
	s_waitcnt lgkmcnt(0)
	v_lshl_add_u32 v2, v2, 10, v204
	global_load_dwordx4 v[58:61], v2, s[98:99]
	ds_bpermute_b32 v2, v170, v157
	s_cmp_lt_i32 s24, s40
	s_waitcnt lgkmcnt(0)
	v_lshl_add_u32 v2, v2, 10, v204
	global_load_dwordx4 v[54:57], v2, s[98:99]
	ds_bpermute_b32 v2, v171, v157
	s_waitcnt lgkmcnt(0)
	v_lshl_add_u32 v2, v2, 10, v204
	global_load_dwordx4 v[50:53], v2, s[98:99]
	ds_bpermute_b32 v2, v172, v157
	s_waitcnt lgkmcnt(0)
	v_lshl_add_u32 v2, v2, 10, v204
	global_load_dwordx4 v[46:49], v2, s[98:99]
	ds_bpermute_b32 v2, v173, v157
	s_waitcnt lgkmcnt(0)
	v_lshl_add_u32 v2, v2, 10, v204
	global_load_dwordx4 v[42:45], v2, s[98:99]
	ds_bpermute_b32 v2, v175, v157
	s_waitcnt lgkmcnt(0)
	v_lshl_add_u32 v2, v2, 10, v204
	global_load_dwordx4 v[38:41], v2, s[98:99]
	ds_bpermute_b32 v2, v176, v157
	s_waitcnt lgkmcnt(0)
	v_lshl_add_u32 v2, v2, 10, v204
	global_load_dwordx4 v[34:37], v2, s[98:99]
	s_waitcnt vmcnt(22)
	ds_bpermute_b32 v2, v168, v156
	s_waitcnt lgkmcnt(0)
	v_lshl_add_u32 v2, v2, 10, v204
	global_load_dwordx4 v[30:33], v2, s[98:99]
	ds_bpermute_b32 v2, v169, v156
	s_waitcnt lgkmcnt(0)
	v_lshl_add_u32 v2, v2, 10, v204
	global_load_dwordx4 v[26:29], v2, s[98:99]
	ds_bpermute_b32 v2, v170, v156
	s_waitcnt lgkmcnt(0)
	v_lshl_add_u32 v2, v2, 10, v204
	global_load_dwordx4 v[22:25], v2, s[98:99]
	ds_bpermute_b32 v2, v171, v156
	s_waitcnt lgkmcnt(0)
	v_lshl_add_u32 v2, v2, 10, v204
	global_load_dwordx4 v[18:21], v2, s[98:99]
	ds_bpermute_b32 v2, v172, v156
	s_waitcnt lgkmcnt(0)
	v_lshl_add_u32 v2, v2, 10, v204
	global_load_dwordx4 v[14:17], v2, s[98:99]
	ds_bpermute_b32 v2, v173, v156
	s_waitcnt lgkmcnt(0)
	v_lshl_add_u32 v2, v2, 10, v204
	global_load_dwordx4 v[10:13], v2, s[98:99]
	ds_bpermute_b32 v2, v175, v156
	s_waitcnt lgkmcnt(0)
	v_lshl_add_u32 v2, v2, 10, v204
	global_load_dwordx4 v[6:9], v2, s[98:99]
	ds_bpermute_b32 v2, v176, v156
	v_lshl_add_u64 v[156:157], s[26:27], 0, v[154:155]
	global_load_dword v185, v[156:157], off
	v_or_b32_e32 v156, 0x100, v154
	v_mov_b32_e32 v157, s1
	s_waitcnt lgkmcnt(0)
; DI void ev_load(const unsigned char* __restrict__ vb8, const int id0, const int id1, const int cs, const int lane, uint4 (&v)[16]) {
; #pragma unroll
;   for (int i = 0; i < 16; ++i) {
;     const int id = __shfl(i < 8 ? id0 : id1, (8 * i + (lane >> 3)) & 63, 64);
;     v[i] = *(const uint4*)(vb8 + (size_t)id * 1024 + 128 * cs + 16 * (lane & 7));
;   }
; DI void ev_compute(const uint4 (&v)[16], const float c0, const float c1, u16* __restrict__ yrow, const int lane) {
;   f32x2 acc[8];
; #pragma unroll
;   for (int k = 0; k < 8; ++k) acc[k] = f32x2{0.f, 0.f};
; #pragma unroll
;   for (int i = 0; i < 16; ++i) {
;     const float c = __shfl(i < 8 ? c0 : c1, (8 * i + (lane >> 3)) & 63, 64);
;     const f32x2 cc = f32x2{c, c};
;     f32x2 vf[8];
;     fp8x16_to_f32(v[i], vf);
; #pragma unroll
;     for (int k = 0; k < 8; ++k) acc[k] = __builtin_elementwise_fma(vf[k], cc, acc[k]);
;   }
	v_lshl_add_u32 v2, v2, 10, v204
	v_lshl_add_u64 v[158:159], s[26:27], 0, v[156:157]
	v_lshl_add_u64 v[154:155], s[28:29], 0, v[154:155]
	global_load_dwordx4 v[2:5], v2, s[98:99]
	s_nop 0
	global_load_dword v184, v[158:159], off
	global_load_dword v186, v[154:155], off
	v_lshl_add_u64 v[154:155], s[28:29], 0, v[156:157]
	global_load_dword v187, v[154:155], off
	v_cvt_pk_f32_fp8_e32 v[154:155], v126
	v_cvt_pk_f32_fp8_sdwa v[156:157], v126 src0_sel:WORD_1
	v_cvt_pk_f32_fp8_e32 v[158:159], v127
	v_pk_fma_f32 v[126:127], v[154:155], v[164:165], 0 op_sel_hi:[1,0,0]
	v_pk_fma_f32 v[128:129], v[156:157], v[164:165], 0 op_sel_hi:[1,0,0]
	v_pk_fma_f32 v[154:155], v[158:159], v[164:165], 0 op_sel_hi:[1,0,0]
	v_pk_fma_f32 v[156:157], v[160:161], v[164:165], 0 op_sel_hi:[1,0,0]
	v_pk_fma_f32 v[158:159], v[162:163], v[164:165], 0 op_sel_hi:[1,0,0]
	v_pk_fma_f32 v[160:161], v[188:189], v[164:165], 0 op_sel_hi:[1,0,0]
	v_pk_fma_f32 v[162:163], v[190:191], v[164:165], 0 op_sel_hi:[1,0,0]
	v_pk_fma_f32 v[164:165], v[192:193], v[164:165], 0 op_sel_hi:[1,0,0]
	v_cvt_pk_f32_fp8_e32 v[188:189], v122
	v_cvt_pk_f32_fp8_sdwa v[190:191], v122 src0_sel:WORD_1
	v_cvt_pk_f32_fp8_e32 v[192:193], v123
	v_cvt_pk_f32_fp8_sdwa v[122:123], v123 src0_sel:WORD_1
	v_pk_fma_f32 v[126:127], v[188:189], v[166:167], v[126:127] op_sel_hi:[1,0,1]
	v_pk_fma_f32 v[128:129], v[190:191], v[166:167], v[128:129] op_sel_hi:[1,0,1]
	v_pk_fma_f32 v[154:155], v[192:193], v[166:167], v[154:155] op_sel_hi:[1,0,1]
	v_pk_fma_f32 v[122:123], v[122:123], v[166:167], v[156:157] op_sel_hi:[1,0,1]
	v_pk_fma_f32 v[156:157], v[194:195], v[166:167], v[158:159] op_sel_hi:[1,0,1]
	v_pk_fma_f32 v[158:159], v[196:197], v[166:167], v[160:161] op_sel_hi:[1,0,1]
	v_pk_fma_f32 v[160:161], v[198:199], v[166:167], v[162:163] op_sel_hi:[1,0,1]
	ds_bpermute_b32 v162, v170, v183
	v_cvt_pk_f32_fp8_e32 v[192:193], v120
	v_cvt_pk_f32_fp8_sdwa v[194:195], v120 src0_sel:WORD_1
	v_cvt_pk_f32_fp8_e32 v[196:197], v121
	v_cvt_pk_f32_fp8_sdwa v[120:121], v121 src0_sel:WORD_1
	v_pk_fma_f32 v[124:125], v[124:125], v[166:167], v[164:165] op_sel_hi:[1,0,1]
	v_cvt_pk_f32_fp8_e32 v[164:165], v118
	v_cvt_pk_f32_fp8_sdwa v[188:189], v118 src0_sel:WORD_1
	v_cvt_pk_f32_fp8_e32 v[190:191], v119
	v_cvt_pk_f32_fp8_sdwa v[118:119], v119 src0_sel:WORD_1
	s_waitcnt lgkmcnt(0)
	v_pk_fma_f32 v[120:121], v[120:121], v[162:163], v[124:125] op_sel_hi:[1,0,1]
	ds_bpermute_b32 v124, v171, v183
	v_pk_fma_f32 v[128:129], v[188:189], v[162:163], v[128:129] op_sel_hi:[1,0,1]
	v_pk_fma_f32 v[154:155], v[190:191], v[162:163], v[154:155] op_sel_hi:[1,0,1]
	v_pk_fma_f32 v[118:119], v[118:119], v[162:163], v[122:123] op_sel_hi:[1,0,1]
	v_pk_fma_f32 v[122:123], v[192:193], v[162:163], v[156:157] op_sel_hi:[1,0,1]
	s_waitcnt vmcnt(33)
	v_cvt_pk_f32_fp8_e32 v[188:189], v116
	v_cvt_pk_f32_fp8_sdwa v[190:191], v116 src0_sel:WORD_1
	v_cvt_pk_f32_fp8_e32 v[192:193], v117
	v_cvt_pk_f32_fp8_sdwa v[116:117], v117 src0_sel:WORD_1
	v_pk_fma_f32 v[126:127], v[164:165], v[162:163], v[126:127] op_sel_hi:[1,0,1]
	v_pk_fma_f32 v[156:157], v[194:195], v[162:163], v[158:159] op_sel_hi:[1,0,1]
	v_pk_fma_f32 v[158:159], v[196:197], v[162:163], v[160:161] op_sel_hi:[1,0,1]
	v_cvt_pk_f32_fp8_e32 v[160:161], v114
	v_cvt_pk_f32_fp8_sdwa v[162:163], v114 src0_sel:WORD_1
	v_cvt_pk_f32_fp8_e32 v[164:165], v115
	v_cvt_pk_f32_fp8_sdwa v[114:115], v115 src0_sel:WORD_1
	s_waitcnt lgkmcnt(0)
	v_pk_fma_f32 v[116:117], v[116:117], v[124:125], v[120:121] op_sel_hi:[1,0,1]
	ds_bpermute_b32 v120, v172, v183
	v_pk_fma_f32 v[128:129], v[162:163], v[124:125], v[128:129] op_sel_hi:[1,0,1]
	v_pk_fma_f32 v[154:155], v[164:165], v[124:125], v[154:155] op_sel_hi:[1,0,1]
	v_pk_fma_f32 v[114:115], v[114:115], v[124:125], v[118:119] op_sel_hi:[1,0,1]
	v_pk_fma_f32 v[118:119], v[188:189], v[124:125], v[122:123] op_sel_hi:[1,0,1]
	s_waitcnt vmcnt(32)
	v_cvt_pk_f32_fp8_e32 v[162:163], v112
	v_cvt_pk_f32_fp8_sdwa v[164:165], v112 src0_sel:WORD_1
	v_cvt_pk_f32_fp8_e32 v[188:189], v113
	v_cvt_pk_f32_fp8_sdwa v[112:113], v113 src0_sel:WORD_1
	v_pk_fma_f32 v[126:127], v[160:161], v[124:125], v[126:127] op_sel_hi:[1,0,1]
	v_pk_fma_f32 v[122:123], v[190:191], v[124:125], v[156:157] op_sel_hi:[1,0,1]
	v_pk_fma_f32 v[156:157], v[192:193], v[124:125], v[158:159] op_sel_hi:[1,0,1]
	v_cvt_pk_f32_fp8_e32 v[124:125], v110
	v_cvt_pk_f32_fp8_sdwa v[158:159], v110 src0_sel:WORD_1
	v_cvt_pk_f32_fp8_e32 v[160:161], v111
	v_cvt_pk_f32_fp8_sdwa v[110:111], v111 src0_sel:WORD_1
	s_waitcnt lgkmcnt(0)
	v_pk_fma_f32 v[112:113], v[112:113], v[120:121], v[116:117] op_sel_hi:[1,0,1]
	ds_bpermute_b32 v116, v173, v183
	v_pk_fma_f32 v[124:125], v[124:125], v[120:121], v[126:127] op_sel_hi:[1,0,1]
	v_pk_fma_f32 v[126:127], v[158:159], v[120:121], v[128:129] op_sel_hi:[1,0,1]
	v_pk_fma_f32 v[128:129], v[160:161], v[120:121], v[154:155] op_sel_hi:[1,0,1]
	v_pk_fma_f32 v[110:111], v[110:111], v[120:121], v[114:115] op_sel_hi:[1,0,1]
	v_pk_fma_f32 v[114:115], v[162:163], v[120:121], v[118:119] op_sel_hi:[1,0,1]
	s_waitcnt vmcnt(31)
	v_cvt_pk_f32_fp8_e32 v[158:159], v108
	v_cvt_pk_f32_fp8_sdwa v[160:161], v108 src0_sel:WORD_1
	v_cvt_pk_f32_fp8_e32 v[162:163], v109
	v_cvt_pk_f32_fp8_sdwa v[108:109], v109 src0_sel:WORD_1
	v_pk_fma_f32 v[118:119], v[164:165], v[120:121], v[122:123] op_sel_hi:[1,0,1]
	v_pk_fma_f32 v[122:123], v[188:189], v[120:121], v[156:157] op_sel_hi:[1,0,1]
	v_cvt_pk_f32_fp8_e32 v[120:121], v106
	v_cvt_pk_f32_fp8_sdwa v[154:155], v106 src0_sel:WORD_1
	v_cvt_pk_f32_fp8_e32 v[156:157], v107
	v_cvt_pk_f32_fp8_sdwa v[106:107], v107 src0_sel:WORD_1
	s_waitcnt lgkmcnt(0)
; DI void ev_compute(const uint4 (&v)[16], const float c0, const float c1, u16* __restrict__ yrow, const int lane) {
;     ...
;   for (int i = 0; i < 16; ++i) {
;     const float c = __shfl(i < 8 ? c0 : c1, (8 * i + (lane >> 3)) & 63, 64);
;     const f32x2 cc = f32x2{c, c};
;     f32x2 vf[8];
;     fp8x16_to_f32(v[i], vf);
; #pragma unroll
;     for (int k = 0; k < 8; ++k) acc[k] = __builtin_elementwise_fma(vf[k], cc, acc[k]);
;   }
	v_pk_fma_f32 v[108:109], v[108:109], v[116:117], v[112:113] op_sel_hi:[1,0,1]
	ds_bpermute_b32 v112, v175, v183
	v_pk_fma_f32 v[120:121], v[120:121], v[116:117], v[124:125] op_sel_hi:[1,0,1]
	v_pk_fma_f32 v[124:125], v[154:155], v[116:117], v[126:127] op_sel_hi:[1,0,1]
	v_pk_fma_f32 v[126:127], v[156:157], v[116:117], v[128:129] op_sel_hi:[1,0,1]
	v_pk_fma_f32 v[106:107], v[106:107], v[116:117], v[110:111] op_sel_hi:[1,0,1]
	v_pk_fma_f32 v[110:111], v[158:159], v[116:117], v[114:115] op_sel_hi:[1,0,1]
	s_waitcnt vmcnt(30)
	v_cvt_pk_f32_fp8_e32 v[154:155], v104
	v_cvt_pk_f32_fp8_sdwa v[156:157], v104 src0_sel:WORD_1
	v_cvt_pk_f32_fp8_e32 v[158:159], v105
	v_cvt_pk_f32_fp8_sdwa v[104:105], v105 src0_sel:WORD_1
	v_pk_fma_f32 v[114:115], v[160:161], v[116:117], v[118:119] op_sel_hi:[1,0,1]
	v_pk_fma_f32 v[118:119], v[162:163], v[116:117], v[122:123] op_sel_hi:[1,0,1]
	v_cvt_pk_f32_fp8_e32 v[116:117], v102
	v_cvt_pk_f32_fp8_sdwa v[122:123], v102 src0_sel:WORD_1
	v_cvt_pk_f32_fp8_e32 v[128:129], v103
	v_cvt_pk_f32_fp8_sdwa v[102:103], v103 src0_sel:WORD_1
	s_waitcnt lgkmcnt(0)
	v_pk_fma_f32 v[104:105], v[104:105], v[112:113], v[108:109] op_sel_hi:[1,0,1]
	ds_bpermute_b32 v108, v176, v183
	v_pk_fma_f32 v[116:117], v[116:117], v[112:113], v[120:121] op_sel_hi:[1,0,1]
	v_pk_fma_f32 v[120:121], v[122:123], v[112:113], v[124:125] op_sel_hi:[1,0,1]
	v_pk_fma_f32 v[122:123], v[128:129], v[112:113], v[126:127] op_sel_hi:[1,0,1]
	v_pk_fma_f32 v[102:103], v[102:103], v[112:113], v[106:107] op_sel_hi:[1,0,1]
	v_pk_fma_f32 v[106:107], v[154:155], v[112:113], v[110:111] op_sel_hi:[1,0,1]
	s_waitcnt vmcnt(29)
	v_cvt_pk_f32_fp8_e32 v[126:127], v100
	v_cvt_pk_f32_fp8_sdwa v[128:129], v100 src0_sel:WORD_1
	v_cvt_pk_f32_fp8_e32 v[154:155], v101
	v_cvt_pk_f32_fp8_sdwa v[100:101], v101 src0_sel:WORD_1
	v_pk_fma_f32 v[110:111], v[156:157], v[112:113], v[114:115] op_sel_hi:[1,0,1]
	v_pk_fma_f32 v[114:115], v[158:159], v[112:113], v[118:119] op_sel_hi:[1,0,1]
	v_cvt_pk_f32_fp8_e32 v[112:113], v98
	v_cvt_pk_f32_fp8_sdwa v[118:119], v98 src0_sel:WORD_1
	v_cvt_pk_f32_fp8_e32 v[124:125], v99
	v_cvt_pk_f32_fp8_sdwa v[98:99], v99 src0_sel:WORD_1
	s_waitcnt lgkmcnt(0)
	v_pk_fma_f32 v[100:101], v[100:101], v[108:109], v[104:105] op_sel_hi:[1,0,1]
	ds_bpermute_b32 v104, v168, v180
	v_pk_fma_f32 v[112:113], v[112:113], v[108:109], v[116:117] op_sel_hi:[1,0,1]
	v_pk_fma_f32 v[116:117], v[118:119], v[108:109], v[120:121] op_sel_hi:[1,0,1]
	v_pk_fma_f32 v[118:119], v[124:125], v[108:109], v[122:123] op_sel_hi:[1,0,1]
	v_pk_fma_f32 v[98:99], v[98:99], v[108:109], v[102:103] op_sel_hi:[1,0,1]
	v_pk_fma_f32 v[102:103], v[126:127], v[108:109], v[106:107] op_sel_hi:[1,0,1]
	s_waitcnt vmcnt(28)
	v_cvt_pk_f32_fp8_e32 v[122:123], v96
	v_cvt_pk_f32_fp8_sdwa v[124:125], v96 src0_sel:WORD_1
	v_cvt_pk_f32_fp8_e32 v[126:127], v97
	v_cvt_pk_f32_fp8_sdwa v[96:97], v97 src0_sel:WORD_1
	v_pk_fma_f32 v[106:107], v[128:129], v[108:109], v[110:111] op_sel_hi:[1,0,1]
	v_pk_fma_f32 v[110:111], v[154:155], v[108:109], v[114:115] op_sel_hi:[1,0,1]
	v_cvt_pk_f32_fp8_e32 v[108:109], v94
	v_cvt_pk_f32_fp8_sdwa v[114:115], v94 src0_sel:WORD_1
	v_cvt_pk_f32_fp8_e32 v[120:121], v95
	v_cvt_pk_f32_fp8_sdwa v[94:95], v95 src0_sel:WORD_1
	s_waitcnt lgkmcnt(0)
	v_pk_fma_f32 v[96:97], v[96:97], v[104:105], v[100:101] op_sel_hi:[1,0,1]
	ds_bpermute_b32 v100, v169, v180
	v_pk_fma_f32 v[108:109], v[108:109], v[104:105], v[112:113] op_sel_hi:[1,0,1]
	v_pk_fma_f32 v[112:113], v[114:115], v[104:105], v[116:117] op_sel_hi:[1,0,1]
	v_pk_fma_f32 v[114:115], v[120:121], v[104:105], v[118:119] op_sel_hi:[1,0,1]
	v_pk_fma_f32 v[94:95], v[94:95], v[104:105], v[98:99] op_sel_hi:[1,0,1]
	v_pk_fma_f32 v[98:99], v[122:123], v[104:105], v[102:103] op_sel_hi:[1,0,1]
	s_waitcnt vmcnt(27)
	v_cvt_pk_f32_fp8_e32 v[118:119], v92
	v_cvt_pk_f32_fp8_sdwa v[120:121], v92 src0_sel:WORD_1
	v_cvt_pk_f32_fp8_e32 v[122:123], v93
	v_cvt_pk_f32_fp8_sdwa v[92:93], v93 src0_sel:WORD_1
	v_pk_fma_f32 v[102:103], v[124:125], v[104:105], v[106:107] op_sel_hi:[1,0,1]
	v_pk_fma_f32 v[106:107], v[126:127], v[104:105], v[110:111] op_sel_hi:[1,0,1]
	v_cvt_pk_f32_fp8_e32 v[104:105], v90
	v_cvt_pk_f32_fp8_sdwa v[110:111], v90 src0_sel:WORD_1
	v_cvt_pk_f32_fp8_e32 v[116:117], v91
	v_cvt_pk_f32_fp8_sdwa v[90:91], v91 src0_sel:WORD_1
	s_waitcnt lgkmcnt(0)
	v_pk_fma_f32 v[92:93], v[92:93], v[100:101], v[96:97] op_sel_hi:[1,0,1]
	ds_bpermute_b32 v96, v170, v180
	v_pk_fma_f32 v[104:105], v[104:105], v[100:101], v[108:109] op_sel_hi:[1,0,1]
	v_pk_fma_f32 v[108:109], v[110:111], v[100:101], v[112:113] op_sel_hi:[1,0,1]
	v_pk_fma_f32 v[110:111], v[116:117], v[100:101], v[114:115] op_sel_hi:[1,0,1]
	v_pk_fma_f32 v[90:91], v[90:91], v[100:101], v[94:95] op_sel_hi:[1,0,1]
	v_pk_fma_f32 v[94:95], v[118:119], v[100:101], v[98:99] op_sel_hi:[1,0,1]
	s_waitcnt vmcnt(26)
	v_cvt_pk_f32_fp8_e32 v[114:115], v88
	v_cvt_pk_f32_fp8_sdwa v[116:117], v88 src0_sel:WORD_1
	v_cvt_pk_f32_fp8_e32 v[118:119], v89
	v_cvt_pk_f32_fp8_sdwa v[88:89], v89 src0_sel:WORD_1
	v_pk_fma_f32 v[98:99], v[120:121], v[100:101], v[102:103] op_sel_hi:[1,0,1]
	v_pk_fma_f32 v[102:103], v[122:123], v[100:101], v[106:107] op_sel_hi:[1,0,1]
	v_cvt_pk_f32_fp8_e32 v[100:101], v86
	v_cvt_pk_f32_fp8_sdwa v[106:107], v86 src0_sel:WORD_1
	v_cvt_pk_f32_fp8_e32 v[112:113], v87
	v_cvt_pk_f32_fp8_sdwa v[86:87], v87 src0_sel:WORD_1
	s_waitcnt lgkmcnt(0)
	v_pk_fma_f32 v[88:89], v[88:89], v[96:97], v[92:93] op_sel_hi:[1,0,1]
	ds_bpermute_b32 v92, v171, v180
	v_pk_fma_f32 v[100:101], v[100:101], v[96:97], v[104:105] op_sel_hi:[1,0,1]
	v_pk_fma_f32 v[104:105], v[106:107], v[96:97], v[108:109] op_sel_hi:[1,0,1]
	v_pk_fma_f32 v[106:107], v[112:113], v[96:97], v[110:111] op_sel_hi:[1,0,1]
	v_pk_fma_f32 v[86:87], v[86:87], v[96:97], v[90:91] op_sel_hi:[1,0,1]
	v_pk_fma_f32 v[90:91], v[114:115], v[96:97], v[94:95] op_sel_hi:[1,0,1]
	s_waitcnt vmcnt(25)
; DI unsigned pack2(float a, float b) { const f32x2 v = {a, b}; const bf16x2_t r = __builtin_convertvector(v, bf16x2_t); return __builtin_bit_cast(unsigned, r); }
; DI void ev_compute(const uint4 (&v)[16], const float c0, const float c1, u16* __restrict__ yrow, const int lane) {
;     ...
;   for (int i = 0; i < 16; ++i) {
;     const float c = __shfl(i < 8 ? c0 : c1, (8 * i + (lane >> 3)) & 63, 64);
;     const f32x2 cc = f32x2{c, c};
;     f32x2 vf[8];
;     fp8x16_to_f32(v[i], vf);
; #pragma unroll
;     for (int k = 0; k < 8; ++k) acc[k] = __builtin_elementwise_fma(vf[k], cc, acc[k]);
;   }
;   float a[16];
; #pragma unroll
;   for (int k = 0; k < 8; ++k) { a[2 * k] = acc[k][0]; a[2 * k + 1] = acc[k][1]; }
;   float q8[8], q4[4], q2[2];
;   const bool b5 = lane & 32, b4 = lane & 16, b3 = lane & 8;
; #pragma unroll
;   for (int j = 0; j < 8; ++j) { const float keep = b5 ? a[8 + j] : a[j], send = b5 ? a[j] : a[8 + j]; q8[j] = keep + __shfl_xor(send, 32, 64); }
; #pragma unroll
;   for (int j = 0; j < 4; ++j) { const float keep = b4 ? q8[4 + j] : q8[j], send = b4 ? q8[j] : q8[4 + j]; q4[j] = keep + __shfl_xor(send, 16, 64); }
; #pragma unroll
;   for (int j = 0; j < 2; ++j) { const float keep = b3 ? q4[2 + j] : q4[j], send = b3 ? q4[j] : q4[2 + j]; q2[j] = keep + __shfl_xor(send, 8, 64); }
;   *(unsigned*)(yrow + 16 * (lane & 7) + 2 * (lane >> 3)) = pack2(q2[0], q2[1]);
; }
	v_cvt_pk_f32_fp8_e32 v[110:111], v84
	v_cvt_pk_f32_fp8_sdwa v[112:113], v84 src0_sel:WORD_1
	v_cvt_pk_f32_fp8_e32 v[114:115], v85
	v_cvt_pk_f32_fp8_sdwa v[84:85], v85 src0_sel:WORD_1
	v_pk_fma_f32 v[94:95], v[116:117], v[96:97], v[98:99] op_sel_hi:[1,0,1]
	v_pk_fma_f32 v[98:99], v[118:119], v[96:97], v[102:103] op_sel_hi:[1,0,1]
	v_cvt_pk_f32_fp8_e32 v[96:97], v82
	v_cvt_pk_f32_fp8_sdwa v[102:103], v82 src0_sel:WORD_1
	v_cvt_pk_f32_fp8_e32 v[108:109], v83
	v_cvt_pk_f32_fp8_sdwa v[82:83], v83 src0_sel:WORD_1
	s_waitcnt lgkmcnt(0)
	v_pk_fma_f32 v[84:85], v[84:85], v[92:93], v[88:89] op_sel_hi:[1,0,1]
	ds_bpermute_b32 v88, v172, v180
	v_pk_fma_f32 v[96:97], v[96:97], v[92:93], v[100:101] op_sel_hi:[1,0,1]
	v_pk_fma_f32 v[100:101], v[102:103], v[92:93], v[104:105] op_sel_hi:[1,0,1]
	v_pk_fma_f32 v[102:103], v[108:109], v[92:93], v[106:107] op_sel_hi:[1,0,1]
	v_pk_fma_f32 v[82:83], v[82:83], v[92:93], v[86:87] op_sel_hi:[1,0,1]
	v_pk_fma_f32 v[86:87], v[110:111], v[92:93], v[90:91] op_sel_hi:[1,0,1]
	s_waitcnt vmcnt(24)
	v_cvt_pk_f32_fp8_e32 v[106:107], v80
	v_cvt_pk_f32_fp8_sdwa v[108:109], v80 src0_sel:WORD_1
	v_cvt_pk_f32_fp8_e32 v[110:111], v81
	v_cvt_pk_f32_fp8_sdwa v[80:81], v81 src0_sel:WORD_1
	v_pk_fma_f32 v[90:91], v[112:113], v[92:93], v[94:95] op_sel_hi:[1,0,1]
	v_pk_fma_f32 v[94:95], v[114:115], v[92:93], v[98:99] op_sel_hi:[1,0,1]
	v_cvt_pk_f32_fp8_e32 v[92:93], v78
	v_cvt_pk_f32_fp8_sdwa v[98:99], v78 src0_sel:WORD_1
	v_cvt_pk_f32_fp8_e32 v[104:105], v79
	v_cvt_pk_f32_fp8_sdwa v[78:79], v79 src0_sel:WORD_1
	s_waitcnt lgkmcnt(0)
	v_pk_fma_f32 v[80:81], v[80:81], v[88:89], v[84:85] op_sel_hi:[1,0,1]
	ds_bpermute_b32 v84, v173, v180
	v_pk_fma_f32 v[92:93], v[92:93], v[88:89], v[96:97] op_sel_hi:[1,0,1]
	v_pk_fma_f32 v[96:97], v[98:99], v[88:89], v[100:101] op_sel_hi:[1,0,1]
	v_pk_fma_f32 v[98:99], v[104:105], v[88:89], v[102:103] op_sel_hi:[1,0,1]
	v_pk_fma_f32 v[78:79], v[78:79], v[88:89], v[82:83] op_sel_hi:[1,0,1]
	v_pk_fma_f32 v[82:83], v[106:107], v[88:89], v[86:87] op_sel_hi:[1,0,1]
	s_waitcnt vmcnt(23)
	v_cvt_pk_f32_fp8_e32 v[102:103], v76
	v_cvt_pk_f32_fp8_sdwa v[104:105], v76 src0_sel:WORD_1
	v_cvt_pk_f32_fp8_e32 v[106:107], v77
	v_cvt_pk_f32_fp8_sdwa v[76:77], v77 src0_sel:WORD_1
	v_pk_fma_f32 v[86:87], v[108:109], v[88:89], v[90:91] op_sel_hi:[1,0,1]
	v_pk_fma_f32 v[90:91], v[110:111], v[88:89], v[94:95] op_sel_hi:[1,0,1]
	v_cvt_pk_f32_fp8_e32 v[88:89], v74
	v_cvt_pk_f32_fp8_sdwa v[94:95], v74 src0_sel:WORD_1
	v_cvt_pk_f32_fp8_e32 v[100:101], v75
	v_cvt_pk_f32_fp8_sdwa v[74:75], v75 src0_sel:WORD_1
	s_waitcnt lgkmcnt(0)
	v_pk_fma_f32 v[76:77], v[76:77], v[84:85], v[80:81] op_sel_hi:[1,0,1]
	ds_bpermute_b32 v80, v175, v180
	v_pk_fma_f32 v[88:89], v[88:89], v[84:85], v[92:93] op_sel_hi:[1,0,1]
	v_pk_fma_f32 v[92:93], v[94:95], v[84:85], v[96:97] op_sel_hi:[1,0,1]
	v_pk_fma_f32 v[94:95], v[100:101], v[84:85], v[98:99] op_sel_hi:[1,0,1]
	v_pk_fma_f32 v[74:75], v[74:75], v[84:85], v[78:79] op_sel_hi:[1,0,1]
	v_pk_fma_f32 v[78:79], v[102:103], v[84:85], v[82:83] op_sel_hi:[1,0,1]
	s_waitcnt vmcnt(22)
	v_cvt_pk_f32_fp8_e32 v[98:99], v72
	v_cvt_pk_f32_fp8_sdwa v[100:101], v72 src0_sel:WORD_1
	v_cvt_pk_f32_fp8_e32 v[102:103], v73
	v_cvt_pk_f32_fp8_sdwa v[72:73], v73 src0_sel:WORD_1
	v_pk_fma_f32 v[82:83], v[104:105], v[84:85], v[86:87] op_sel_hi:[1,0,1]
	v_pk_fma_f32 v[86:87], v[106:107], v[84:85], v[90:91] op_sel_hi:[1,0,1]
	v_cvt_pk_f32_fp8_e32 v[84:85], v70
	v_cvt_pk_f32_fp8_sdwa v[90:91], v70 src0_sel:WORD_1
	v_cvt_pk_f32_fp8_e32 v[96:97], v71
	v_cvt_pk_f32_fp8_sdwa v[70:71], v71 src0_sel:WORD_1
	s_waitcnt lgkmcnt(0)
	v_pk_fma_f32 v[72:73], v[72:73], v[80:81], v[76:77] op_sel_hi:[1,0,1]
	ds_bpermute_b32 v76, v176, v180
	v_pk_fma_f32 v[84:85], v[84:85], v[80:81], v[88:89] op_sel_hi:[1,0,1]
	v_pk_fma_f32 v[88:89], v[90:91], v[80:81], v[92:93] op_sel_hi:[1,0,1]
	v_pk_fma_f32 v[90:91], v[96:97], v[80:81], v[94:95] op_sel_hi:[1,0,1]
	v_pk_fma_f32 v[70:71], v[70:71], v[80:81], v[74:75] op_sel_hi:[1,0,1]
	v_pk_fma_f32 v[74:75], v[98:99], v[80:81], v[78:79] op_sel_hi:[1,0,1]
	v_pk_fma_f32 v[78:79], v[100:101], v[80:81], v[82:83] op_sel_hi:[1,0,1]
	v_pk_fma_f32 v[82:83], v[102:103], v[80:81], v[86:87] op_sel_hi:[1,0,1]
	s_waitcnt vmcnt(21)
	v_cvt_pk_f32_fp8_e32 v[80:81], v66
	v_cvt_pk_f32_fp8_sdwa v[86:87], v66 src0_sel:WORD_1
	v_cvt_pk_f32_fp8_e32 v[92:93], v67
	v_cvt_pk_f32_fp8_sdwa v[66:67], v67 src0_sel:WORD_1
	v_cvt_pk_f32_fp8_e32 v[94:95], v68
	v_cvt_pk_f32_fp8_sdwa v[96:97], v68 src0_sel:WORD_1
	v_cvt_pk_f32_fp8_e32 v[98:99], v69
	v_cvt_pk_f32_fp8_sdwa v[68:69], v69 src0_sel:WORD_1
	s_waitcnt lgkmcnt(0)
	v_pk_fma_f32 v[80:81], v[80:81], v[76:77], v[84:85] op_sel_hi:[1,0,1]
	v_pk_fma_f32 v[66:67], v[66:67], v[76:77], v[70:71] op_sel_hi:[1,0,1]
	v_pk_fma_f32 v[70:71], v[94:95], v[76:77], v[74:75] op_sel_hi:[1,0,1]
	v_pk_fma_f32 v[84:85], v[86:87], v[76:77], v[88:89] op_sel_hi:[1,0,1]
	v_pk_fma_f32 v[86:87], v[92:93], v[76:77], v[90:91] op_sel_hi:[1,0,1]
	v_pk_fma_f32 v[74:75], v[96:97], v[76:77], v[78:79] op_sel_hi:[1,0,1]
	v_pk_fma_f32 v[78:79], v[98:99], v[76:77], v[82:83] op_sel_hi:[1,0,1]
	v_pk_fma_f32 v[68:69], v[68:69], v[76:77], v[72:73] op_sel_hi:[1,0,1]
	s_nop 1
	v_permlane32_swap_b32_e32 v80, v70
	v_permlane32_swap_b32_e32 v81, v71
	v_permlane32_swap_b32_e32 v84, v74
	v_permlane32_swap_b32_e32 v85, v75
	v_permlane32_swap_b32_e32 v86, v78
	v_permlane32_swap_b32_e32 v87, v79
	v_permlane32_swap_b32_e32 v66, v68
	v_permlane32_swap_b32_e32 v67, v69
	v_pk_add_f32 v[70:71], v[80:81], v[70:71]
	v_pk_add_f32 v[72:73], v[84:85], v[74:75]
	v_pk_add_f32 v[74:75], v[86:87], v[78:79]
	v_pk_add_f32 v[66:67], v[66:67], v[68:69]
	s_nop 1
	v_permlane16_swap_b32_e32 v70, v74
	v_permlane16_swap_b32_e32 v71, v75
	v_permlane16_swap_b32_e32 v72, v66
	v_permlane16_swap_b32_e32 v73, v67
	v_mov_b32_e32 v155, v181
	s_waitcnt lgkmcnt(2)
	v_pk_add_f32 v[68:69], v[70:71], v[74:75]
	v_mov_b32_e32 v154, v182
	s_waitcnt lgkmcnt(0)
	v_pk_add_f32 v[66:67], v[72:73], v[66:67]
	s_waitcnt vmcnt(0)
	v_mov_b32_e32 v180, v187
	v_cndmask_b32_e64 v70, v68, v66, s[10:11]
	v_cndmask_b32_e64 v72, v66, v68, s[10:11]
	v_cndmask_b32_e64 v66, v69, v67, s[10:11]
	ds_bpermute_b32 v70, v179, v70
	ds_bpermute_b32 v71, v179, v66
	v_cndmask_b32_e64 v73, v67, v69, s[10:11]
	v_mov_b32_e32 v183, v186
	s_waitcnt lgkmcnt(0)
	v_pk_add_f32 v[66:67], v[72:73], v[70:71]
	s_nop 0
	v_cvt_pk_bf16_f32 v68, v66, v67
	v_lshl_add_u64 v[66:67], v[152:153], 0, s[30:31]
	s_mov_b32 s30, s34
	global_store_dword v[66:67], v68, off
	s_cbranch_scc1 .LBB0_570
	s_branch .LBB0_566
